# entry grid.sync without L2 write-back / L1 invalidate (only write-through barrier words cross it); all waves drain zeroing stores
# baseline (speedup 1.0000x reference)
; #define LAS __attribute__((address_space(3)))
; __global__ void __launch_bounds__(NTHR, 2) fwd_kernel(Args a) {
;     ...
;     if (threadIdx.x < 64) ((LAS unsigned*)(lds + 131072))[threadIdx.x] = 0u;
;     if (bx == 0) for (int i = threadIdx.x; i < XCD_BAR_WORDS; i += NTHR) __hip_atomic_store((unsigned*)(a.ws + 16384) + i, 0u, __ATOMIC_RELAXED, __HIP_MEMORY_SCOPE_AGENT);
;     __syncthreads();
;     grid.sync();
.LBB0_6:
	v_lshrrev_b32_e32 v1, 20, v0
	v_lshrrev_b32_e32 v0, 10, v0
	v_or_b32_e32 v0, v0, v1
	s_movk_i32 s2, 0x3ff
	v_and_or_b32 v0, v0, s2, v189
	v_cmp_eq_u32_e32 vcc, 0, v0
	s_waitcnt vmcnt(0)
	s_barrier
	s_barrier
	s_and_saveexec_b64 s[2:3], vcc
	s_cbranch_execz .LBB0_16
	s_waitcnt vmcnt(0)
	s_load_dwordx2 s[4:5], s[4:5], 0x58
	v_mov_b32_e32 v2, 0
	s_mov_b64 s[6:7], exec
	v_mbcnt_lo_u32_b32 v1, s6, 0
	v_mbcnt_hi_u32_b32 v1, s7, v1
	s_waitcnt lgkmcnt(0)
	global_load_dword v0, v2, s[4:5] offset:40
	v_cmp_eq_u32_e32 vcc, 0, v1
	s_and_saveexec_b64 s[8:9], vcc
	s_cbranch_execz .LBB0_9
	s_bcnt1_i32_b64 s6, s[6:7]
	v_mov_b32_e32 v3, s6
	global_atomic_add v3, v2, v3, s[4:5] offset:32 sc0

; #define LAS __attribute__((address_space(3)))
; __device__ __forceinline__ unsigned xb_add(unsigned* p, unsigned v) { return __hip_atomic_fetch_add(p, v, __ATOMIC_RELAXED, __HIP_MEMORY_SCOPE_AGENT); }
; __device__ __forceinline__ unsigned xb_xcc_id() { return (unsigned)__builtin_amdgcn_s_getreg((3 << 11) | 20) & 0xFu; }
; __device__ __forceinline__ XcdBarrier xcd_barrier_post(unsigned* bar, volatile LAS unsigned* st) {
;     XcdBarrier b; b.bar = bar; b.x = xb_xcc_id(); b.st = st;
;     if (threadIdx.x == 0) (void)xb_add(&bar[XB_XCNT(b.x)], 1u);
;     return b;
; }
; __global__ void __launch_bounds__(NTHR, 2) fwd_kernel(Args a) {
;     ...
;     grid.sync();
;     const XcdBarrier xbar = xcd_barrier_post((unsigned*)(a.ws + 16384), (volatile LAS unsigned*)(lds + 131072 + 32));
.LBB0_15:
.LBB0_16:
	s_or_b64 exec, exec, s[2:3]
	s_load_dwordx16 s[4:19], s[0:1], 0x0
	s_barrier
	s_waitcnt lgkmcnt(0)
	v_cmp_eq_u32_e64 s[2:3], 0, v189
	v_writelane_b32 v254, s4, 1
	s_nop 1
	v_writelane_b32 v254, s5, 2
	v_writelane_b32 v254, s6, 3
	v_writelane_b32 v254, s7, 4
	v_writelane_b32 v254, s8, 5
	v_writelane_b32 v254, s9, 6
	v_writelane_b32 v254, s10, 7
	v_writelane_b32 v254, s11, 8
	v_writelane_b32 v254, s12, 9
	v_writelane_b32 v254, s13, 10
	v_writelane_b32 v254, s14, 11
	v_writelane_b32 v254, s15, 12
	v_writelane_b32 v254, s16, 13
	v_writelane_b32 v254, s17, 14
	v_writelane_b32 v254, s18, 15
	v_writelane_b32 v254, s19, 16
	s_load_dwordx16 s[4:19], s[0:1], 0x40
	s_add_u32 s0, s66, 0x4000
	s_addc_u32 s1, s67, 0
	s_waitcnt lgkmcnt(0)
	v_writelane_b32 v254, s4, 17
	s_nop 1
	v_writelane_b32 v254, s5, 18
	v_writelane_b32 v254, s6, 19
	v_writelane_b32 v254, s7, 20
	v_writelane_b32 v254, s8, 21
	v_writelane_b32 v254, s9, 22
	v_writelane_b32 v254, s10, 23
	v_writelane_b32 v254, s11, 24
	v_writelane_b32 v254, s12, 25
	v_writelane_b32 v254, s13, 26
	v_writelane_b32 v254, s14, 27
	v_writelane_b32 v254, s15, 28
	v_writelane_b32 v254, s16, 29
	v_writelane_b32 v254, s17, 30
	v_writelane_b32 v254, s18, 31
	v_writelane_b32 v254, s19, 32
	v_writelane_b32 v254, s0, 33
	s_nop 1
	v_writelane_b32 v254, s1, 34
	s_getreg_b32 s0, hwreg(HW_REG_XCC_ID, 0, 4)
	s_and_b32 s85, s0, 15
	s_mov_b64 s[0:1], exec
	v_writelane_b32 v254, s2, 35
	s_nop 1
	v_writelane_b32 v254, s3, 36
	s_and_b64 s[2:3], s[0:1], s[2:3]
	s_mov_b64 exec, s[2:3]
	s_cbranch_execz .LBB0_19
	s_mov_b64 s[2:3], exec
	v_mbcnt_lo_u32_b32 v0, s2, 0
	v_mbcnt_hi_u32_b32 v0, s3, v0
	v_cmp_eq_u32_e32 vcc, 0, v0
	s_and_b64 s[4:5], exec, vcc
	s_mov_b64 exec, s[4:5]
	s_cbranch_execz .LBB0_19
	s_bcnt1_i32_b64 s2, s[2:3]
	s_lshl_b32 s4, s85, 8
	v_mov_b32_e32 v1, s2
	v_readlane_b32 s2, v254, 33
	v_mov_b32_e32 v0, s4
	v_readlane_b32 s3, v254, 34
	s_nop 4
	global_atomic_add v0, v1, s[2:3] offset:1024
